# v12 with the P6 loop's A-half refill ordered before the other refill of its segment (wait counts now cover it)
# speedup vs baseline: 1.0083x; 1.0083x over previous
; #define PG8_STAGE(bufoff, gbase, voff) do { _Pragma("unroll") for (int _i = 0; _i < 2; ++_i) \
;         __builtin_amdgcn_global_load_lds((const unsigned*)((const char*)(gbase) + (voff)[_i]), (PG8_LAS unsigned*)(lds + (bufoff) + ldsw + _i * 8192), 16, 0, 0); } while (0)
; #define PG8_LDA(dst, b, h) do { _Pragma("unroll") for (int m = 0; m < 4; ++m) _Pragma("unroll") for (int k = 0; k < 2; ++k) dst[m][k] = *(const PG8_LAS bf16x8*)(lds + PG8_SA(b, h) + aoff + m * 2048 + k * 1024); } while (0)
; #define PG8_LDB(dst, b, h) do { _Pragma("unroll") for (int n = 0; n < 2; ++n) _Pragma("unroll") for (int k = 0; k < 2; ++k) dst[n][k] = *(const PG8_LAS bf16x8*)(lds + PG8_SB(b, h) + boff + n * 2048 + k * 1024); } while (0)
; #define PG8_MMA(ai, bj, At, Bt) do { __builtin_amdgcn_s_setprio(1); _Pragma("unroll") for (int m = 0; m < 4; ++m) _Pragma("unroll") for (int n = 0; n < 2; ++n) _Pragma("unroll") for (int k = 0; k < 2; ++k) \
;         acc[ai][bj][m][n] = __builtin_amdgcn_mfma_f32_16x16x32_bf16(Bt[n][k], At[m][k], acc[ai][bj][m][n], 0, 0, 0); __builtin_amdgcn_s_setprio(0); } while (0)
; #define PG8_WAIT_V(n) asm volatile("s_waitcnt vmcnt(" #n ")" ::: "memory")
; #define PG8_WAIT_L(n) asm volatile("s_waitcnt lgkmcnt(" #n ")" ::: "memory")
; #define PG8_BAR __builtin_amdgcn_s_barrier()
; #define PG8_SCHED __builtin_amdgcn_sched_barrier(0)
; template <class Epi, class Sched, bool ALIGN_EPI = false, bool SP2 = false>
; __device__ __forceinline__ void gemm_phase(PG8_LAS unsigned char* lds, const Gemm g, const Sched& S, const Epi& E) {
;     ...
;             PG8_LDB(B0, 0, 0); PG8_LDB(B1, 0, 1); PG8_SCHED; PG8_LDA(At, 0, 0); PG8_STAGE(PG8_SA(1, 1), a1 + hA, voffA);
;             PG8_WAIT_V(8); PG8_WAIT_L(0); PG8_BAR; PG8_MMA(0, 0, At, B0); PG8_MMA(0, 1, At, B1); PG8_BAR; PG8_SCHED;
;             PG8_LDA(At, 0, 1); PG8_STAGE(PG8_SB(0, 0), b2, voffB); PG8_STAGE(PG8_SB(0, 1), b2 + hB, voffB); PG8_STAGE(PG8_SA(0, 0), a2, voffA);
;             PG8_WAIT_V(8); PG8_WAIT_L(0); PG8_BAR; PG8_MMA(1, 0, At, B0); PG8_MMA(1, 1, At, B1); PG8_BAR; PG8_SCHED;
.LBB0_1127:
	ds_read_b128 v[130:133], v190
	ds_read_b128 v[134:137], v190 offset:1024
	ds_read_b128 v[138:141], v190 offset:2048
	ds_read_b128 v[142:145], v190 offset:3072
	ds_read_b128 v[146:149], v191
	ds_read_b128 v[150:153], v191 offset:1024
	ds_read_b128 v[170:173], v191 offset:2048
	ds_read_b128 v[174:177], v191 offset:3072
	s_add_u32 s36, s24, 0x100
	s_addc_u32 s37, s25, 0
	s_cmpk_eq_i32 s63, 0x54
	s_cselect_b32 s41, s9, s37
	s_cselect_b32 s40, s8, s36
	s_cselect_b32 s39, s23, s62
	s_cselect_b32 s38, s22, s61
	s_add_i32 m0, s46, 0xc000
	ds_read_b128 v[178:181], v192
	ds_read_b128 v[182:185], v192 offset:1024
	ds_read_b128 v[194:197], v192 offset:2048
	ds_read_b128 v[198:201], v192 offset:3072
	ds_read_b128 v[202:205], v192 offset:4096
	ds_read_b128 v[206:209], v192 offset:5120
	ds_read_b128 v[210:213], v192 offset:6144
	ds_read_b128 v[214:217], v192 offset:7168
	global_load_lds_dwordx4 v162, s[24:25]
	s_add_i32 m0, s46, 0xe000
	s_nop 0
	global_load_lds_dwordx4 v164, s[24:25]
	s_mov_b32 m0, s52
	s_nop 0
	global_load_lds_dwordx4 v154, s[78:79]
	s_mov_b32 m0, s53
	s_nop 0
	global_load_lds_dwordx4 v158, s[78:79]
	s_waitcnt lgkmcnt(0)
	s_barrier
	s_waitcnt lgkmcnt(0)
	v_mfma_f32_16x16x32_bf16 v[126:129], v[130:133], v[178:181], v[126:129]
	v_mfma_f32_16x16x32_bf16 v[122:125], v[138:141], v[178:181], v[122:125]
	v_mfma_f32_16x16x32_bf16 v[110:113], v[130:133], v[194:197], v[110:113]
	v_mfma_f32_16x16x32_bf16 v[106:109], v[138:141], v[194:197], v[106:109]
	v_mfma_f32_16x16x32_bf16 v[94:97], v[130:133], v[202:205], v[94:97]
	v_mfma_f32_16x16x32_bf16 v[90:93], v[138:141], v[202:205], v[90:93]
	v_mfma_f32_16x16x32_bf16 v[78:81], v[130:133], v[210:213], v[78:81]
	v_mfma_f32_16x16x32_bf16 v[74:77], v[138:141], v[210:213], v[74:77]
	v_mfma_f32_16x16x32_bf16 v[126:129], v[134:137], v[182:185], v[126:129]
	v_mfma_f32_16x16x32_bf16 v[122:125], v[142:145], v[182:185], v[122:125]
	v_mfma_f32_16x16x32_bf16 v[110:113], v[134:137], v[198:201], v[110:113]
	v_mfma_f32_16x16x32_bf16 v[106:109], v[142:145], v[198:201], v[106:109]
	v_mfma_f32_16x16x32_bf16 v[94:97], v[134:137], v[206:209], v[94:97]
	v_mfma_f32_16x16x32_bf16 v[90:93], v[142:145], v[206:209], v[90:93]
	v_mfma_f32_16x16x32_bf16 v[78:81], v[134:137], v[214:217], v[78:81]
	v_mfma_f32_16x16x32_bf16 v[74:77], v[142:145], v[214:217], v[74:77]
	v_mfma_f32_16x16x32_bf16 v[118:121], v[146:149], v[178:181], v[118:121]
	v_mfma_f32_16x16x32_bf16 v[114:117], v[170:173], v[178:181], v[114:117]
	v_mfma_f32_16x16x32_bf16 v[102:105], v[146:149], v[194:197], v[102:105]
	v_mfma_f32_16x16x32_bf16 v[98:101], v[170:173], v[194:197], v[98:101]
	v_mfma_f32_16x16x32_bf16 v[86:89], v[146:149], v[202:205], v[86:89]
	v_mfma_f32_16x16x32_bf16 v[82:85], v[170:173], v[202:205], v[82:85]
	v_mfma_f32_16x16x32_bf16 v[70:73], v[146:149], v[210:213], v[70:73]
	v_mfma_f32_16x16x32_bf16 v[66:69], v[170:173], v[210:213], v[66:69]
	v_mfma_f32_16x16x32_bf16 v[118:121], v[150:153], v[182:185], v[118:121]
	v_mfma_f32_16x16x32_bf16 v[114:117], v[174:177], v[182:185], v[114:117]
	v_mfma_f32_16x16x32_bf16 v[102:105], v[150:153], v[198:201], v[102:105]
	v_mfma_f32_16x16x32_bf16 v[98:101], v[174:177], v[198:201], v[98:101]
	v_mfma_f32_16x16x32_bf16 v[86:89], v[150:153], v[206:209], v[86:89]
	v_mfma_f32_16x16x32_bf16 v[82:85], v[174:177], v[206:209], v[82:85]
	v_mfma_f32_16x16x32_bf16 v[70:73], v[150:153], v[214:217], v[70:73]
	v_mfma_f32_16x16x32_bf16 v[66:69], v[174:177], v[214:217], v[66:69]
	s_waitcnt vmcnt(8)
	s_barrier
	s_add_i32 s18, s55, s45
	s_add_u32 s76, s38, s16
	s_addc_u32 s77, s39, s17
	s_mov_b32 m0, s18
	ds_read_b128 v[178:181], v192 offset:16384
	ds_read_b128 v[182:185], v192 offset:17408
	ds_read_b128 v[194:197], v192 offset:18432
	ds_read_b128 v[198:201], v192 offset:19456
	ds_read_b128 v[202:205], v192 offset:20480
	ds_read_b128 v[206:209], v192 offset:21504
	ds_read_b128 v[210:213], v192 offset:22528
	ds_read_b128 v[214:217], v192 offset:23552
	global_load_lds_dwordx4 v156, s[38:39]
	s_add_i32 m0, s18, 0x2000
	s_add_u32 s24, s38, 0x160000
	s_addc_u32 s25, s39, 0
	s_add_i32 s18, s56, s45
	global_load_lds_dwordx4 v160, s[38:39]
	s_mov_b32 m0, s18
	s_nop 0
	global_load_lds_dwordx4 v156, s[24:25]
	s_add_i32 m0, s18, 0x2000
	s_nop 0
	global_load_lds_dwordx4 v160, s[24:25]
	s_add_u32 s78, s40, s16
	s_addc_u32 s79, s41, s17
	s_waitcnt lgkmcnt(0)
	s_barrier
	s_waitcnt lgkmcnt(0)
	v_mfma_f32_16x16x32_bf16 v[62:65], v[130:133], v[178:181], v[62:65]
	v_mfma_f32_16x16x32_bf16 v[58:61], v[138:141], v[178:181], v[58:61]
	v_mfma_f32_16x16x32_bf16 v[46:49], v[130:133], v[194:197], v[46:49]
	v_mfma_f32_16x16x32_bf16 v[42:45], v[138:141], v[194:197], v[42:45]
	v_mfma_f32_16x16x32_bf16 v[30:33], v[130:133], v[202:205], v[30:33]
	v_mfma_f32_16x16x32_bf16 v[26:29], v[138:141], v[202:205], v[26:29]
	v_mfma_f32_16x16x32_bf16 v[14:17], v[130:133], v[210:213], v[14:17]
	v_mfma_f32_16x16x32_bf16 v[10:13], v[138:141], v[210:213], v[10:13]
	v_mfma_f32_16x16x32_bf16 v[62:65], v[134:137], v[182:185], v[62:65]
	v_mfma_f32_16x16x32_bf16 v[58:61], v[142:145], v[182:185], v[58:61]
	v_mfma_f32_16x16x32_bf16 v[46:49], v[134:137], v[198:201], v[46:49]
	v_mfma_f32_16x16x32_bf16 v[42:45], v[142:145], v[198:201], v[42:45]
	v_mfma_f32_16x16x32_bf16 v[30:33], v[134:137], v[206:209], v[30:33]
	v_mfma_f32_16x16x32_bf16 v[26:29], v[142:145], v[206:209], v[26:29]
	v_mfma_f32_16x16x32_bf16 v[14:17], v[134:137], v[214:217], v[14:17]
	v_mfma_f32_16x16x32_bf16 v[10:13], v[142:145], v[214:217], v[10:13]
	v_mfma_f32_16x16x32_bf16 v[54:57], v[146:149], v[178:181], v[54:57]
	v_mfma_f32_16x16x32_bf16 v[50:53], v[170:173], v[178:181], v[50:53]
	v_mfma_f32_16x16x32_bf16 v[38:41], v[146:149], v[194:197], v[38:41]
	v_mfma_f32_16x16x32_bf16 v[34:37], v[170:173], v[194:197], v[34:37]
	v_mfma_f32_16x16x32_bf16 v[22:25], v[146:149], v[202:205], v[22:25]
	v_mfma_f32_16x16x32_bf16 v[18:21], v[170:173], v[202:205], v[18:21]
	v_mfma_f32_16x16x32_bf16 v[6:9], v[146:149], v[210:213], v[6:9]
	v_mfma_f32_16x16x32_bf16 v[2:5], v[170:173], v[210:213], v[2:5]
	v_mfma_f32_16x16x32_bf16 v[54:57], v[150:153], v[182:185], v[54:57]
	v_mfma_f32_16x16x32_bf16 v[50:53], v[174:177], v[182:185], v[50:53]
	v_mfma_f32_16x16x32_bf16 v[38:41], v[150:153], v[198:201], v[38:41]
	v_mfma_f32_16x16x32_bf16 v[34:37], v[174:177], v[198:201], v[34:37]
	v_mfma_f32_16x16x32_bf16 v[22:25], v[150:153], v[206:209], v[22:25]
	v_mfma_f32_16x16x32_bf16 v[18:21], v[174:177], v[206:209], v[18:21]
	v_mfma_f32_16x16x32_bf16 v[6:9], v[150:153], v[214:217], v[6:9]
	v_mfma_f32_16x16x32_bf16 v[2:5], v[174:177], v[214:217], v[2:5]
	s_waitcnt vmcnt(4)
	s_barrier
; #define PG8_STAGE(bufoff, gbase, voff) do { _Pragma("unroll") for (int _i = 0; _i < 2; ++_i) \
;         __builtin_amdgcn_global_load_lds((const unsigned*)((const char*)(gbase) + (voff)[_i]), (PG8_LAS unsigned*)(lds + (bufoff) + ldsw + _i * 8192), 16, 0, 0); } while (0)
; #define PG8_LDA(dst, b, h) do { _Pragma("unroll") for (int m = 0; m < 4; ++m) _Pragma("unroll") for (int k = 0; k < 2; ++k) dst[m][k] = *(const PG8_LAS bf16x8*)(lds + PG8_SA(b, h) + aoff + m * 2048 + k * 1024); } while (0)
; #define PG8_LDB(dst, b, h) do { _Pragma("unroll") for (int n = 0; n < 2; ++n) _Pragma("unroll") for (int k = 0; k < 2; ++k) dst[n][k] = *(const PG8_LAS bf16x8*)(lds + PG8_SB(b, h) + boff + n * 2048 + k * 1024); } while (0)
; #define PG8_MMA(ai, bj, At, Bt) do { __builtin_amdgcn_s_setprio(1); _Pragma("unroll") for (int m = 0; m < 4; ++m) _Pragma("unroll") for (int n = 0; n < 2; ++n) _Pragma("unroll") for (int k = 0; k < 2; ++k) \
;         acc[ai][bj][m][n] = __builtin_amdgcn_mfma_f32_16x16x32_bf16(Bt[n][k], At[m][k], acc[ai][bj][m][n], 0, 0, 0); __builtin_amdgcn_s_setprio(0); } while (0)
; #define PG8_WAIT_V(n) asm volatile("s_waitcnt vmcnt(" #n ")" ::: "memory")
; #define PG8_WAIT_L(n) asm volatile("s_waitcnt lgkmcnt(" #n ")" ::: "memory")
; #define PG8_BAR __builtin_amdgcn_s_barrier()
; #define PG8_SCHED __builtin_amdgcn_sched_barrier(0)
; template <class Epi, class Sched, bool ALIGN_EPI = false, bool SP2 = false>
; __device__ __forceinline__ void gemm_phase(PG8_LAS unsigned char* lds, const Gemm g, const Sched& S, const Epi& E) {
;     ...
;             PG8_LDB(B0, 1, 0); PG8_LDB(B1, 1, 1); PG8_SCHED; PG8_LDA(At, 1, 0); PG8_STAGE(PG8_SA(0, 1), a2 + hA, voffA);
;             PG8_WAIT_V(8); PG8_WAIT_L(0); PG8_BAR; PG8_MMA(0, 0, At, B0); PG8_MMA(0, 1, At, B1); PG8_BAR; PG8_SCHED;
;             PG8_LDA(At, 1, 1); PG8_STAGE(PG8_SB(1, 0), b3, voffB); PG8_STAGE(PG8_SB(1, 1), b3 + hB, voffB); PG8_STAGE(PG8_SA(1, 0), a3, voffA);
;             PG8_WAIT_V(8); PG8_WAIT_L(0); PG8_BAR; PG8_MMA(1, 0, At, B0); PG8_MMA(1, 1, At, B1); PG8_BAR; PG8_SCHED;
	s_add_i32 s18, 0, 0x18000
	s_add_i32 s19, 0, 0x1c000
	v_add_u32_e32 v142, s18, v188
	v_add_u32_e32 v174, s19, v188
	ds_read_b128 v[130:133], v142
	ds_read_b128 v[134:137], v142 offset:1024
	ds_read_b128 v[138:141], v142 offset:2048
	ds_read_b128 v[142:145], v142 offset:3072
	ds_read_b128 v[146:149], v174
	ds_read_b128 v[150:153], v174 offset:1024
	ds_read_b128 v[170:173], v174 offset:2048
	ds_read_b128 v[174:177], v174 offset:3072
	s_add_u32 s24, s40, 0x160000
	s_addc_u32 s25, s41, 0
	ds_read_b128 v[178:181], v192 offset:32768
	ds_read_b128 v[182:185], v192 offset:33792
	ds_read_b128 v[194:197], v192 offset:34816
	ds_read_b128 v[198:201], v192 offset:35840
	ds_read_b128 v[202:205], v192 offset:36864
	ds_read_b128 v[206:209], v192 offset:37888
	ds_read_b128 v[210:213], v192 offset:38912
	ds_read_b128 v[214:217], v192 offset:39936
	s_mov_b32 m0, s46
	s_nop 0
	global_load_lds_dwordx4 v154, s[40:41]
	s_mov_b32 m0, s47
	s_nop 0
	global_load_lds_dwordx4 v158, s[40:41]
	s_mov_b32 m0, s48
	s_nop 0
	global_load_lds_dwordx4 v154, s[24:25]
	s_mov_b32 m0, s49
	s_nop 0
	global_load_lds_dwordx4 v158, s[24:25]
	s_waitcnt lgkmcnt(0)
	s_barrier
	s_waitcnt lgkmcnt(0)
	v_mfma_f32_16x16x32_bf16 v[126:129], v[130:133], v[178:181], v[126:129]
	v_mfma_f32_16x16x32_bf16 v[122:125], v[138:141], v[178:181], v[122:125]
	v_mfma_f32_16x16x32_bf16 v[110:113], v[130:133], v[194:197], v[110:113]
	v_mfma_f32_16x16x32_bf16 v[106:109], v[138:141], v[194:197], v[106:109]
	v_mfma_f32_16x16x32_bf16 v[94:97], v[130:133], v[202:205], v[94:97]
	v_mfma_f32_16x16x32_bf16 v[90:93], v[138:141], v[202:205], v[90:93]
	v_mfma_f32_16x16x32_bf16 v[78:81], v[130:133], v[210:213], v[78:81]
	v_mfma_f32_16x16x32_bf16 v[74:77], v[138:141], v[210:213], v[74:77]
	v_mfma_f32_16x16x32_bf16 v[126:129], v[134:137], v[182:185], v[126:129]
	v_mfma_f32_16x16x32_bf16 v[122:125], v[142:145], v[182:185], v[122:125]
	v_mfma_f32_16x16x32_bf16 v[110:113], v[134:137], v[198:201], v[110:113]
	v_mfma_f32_16x16x32_bf16 v[106:109], v[142:145], v[198:201], v[106:109]
	v_mfma_f32_16x16x32_bf16 v[94:97], v[134:137], v[206:209], v[94:97]
	v_mfma_f32_16x16x32_bf16 v[90:93], v[142:145], v[206:209], v[90:93]
	v_mfma_f32_16x16x32_bf16 v[78:81], v[134:137], v[214:217], v[78:81]
	v_mfma_f32_16x16x32_bf16 v[74:77], v[142:145], v[214:217], v[74:77]
	v_mfma_f32_16x16x32_bf16 v[118:121], v[146:149], v[178:181], v[118:121]
	v_mfma_f32_16x16x32_bf16 v[114:117], v[170:173], v[178:181], v[114:117]
	v_mfma_f32_16x16x32_bf16 v[102:105], v[146:149], v[194:197], v[102:105]
	v_mfma_f32_16x16x32_bf16 v[98:101], v[170:173], v[194:197], v[98:101]
	v_mfma_f32_16x16x32_bf16 v[86:89], v[146:149], v[202:205], v[86:89]
	v_mfma_f32_16x16x32_bf16 v[82:85], v[170:173], v[202:205], v[82:85]
	v_mfma_f32_16x16x32_bf16 v[70:73], v[146:149], v[210:213], v[70:73]
	v_mfma_f32_16x16x32_bf16 v[66:69], v[170:173], v[210:213], v[66:69]
	v_mfma_f32_16x16x32_bf16 v[118:121], v[150:153], v[182:185], v[118:121]
	v_mfma_f32_16x16x32_bf16 v[114:117], v[174:177], v[182:185], v[114:117]
	v_mfma_f32_16x16x32_bf16 v[102:105], v[150:153], v[198:201], v[102:105]
	v_mfma_f32_16x16x32_bf16 v[98:101], v[174:177], v[198:201], v[98:101]
	v_mfma_f32_16x16x32_bf16 v[86:89], v[150:153], v[206:209], v[86:89]
	v_mfma_f32_16x16x32_bf16 v[82:85], v[174:177], v[206:209], v[82:85]
	v_mfma_f32_16x16x32_bf16 v[70:73], v[150:153], v[214:217], v[70:73]
	v_mfma_f32_16x16x32_bf16 v[66:69], v[174:177], v[214:217], v[66:69]
	s_barrier
	s_add_i32 s18, s18, s45
	s_mov_b32 m0, s18
	ds_read_b128 v[178:181], v192 offset:49152
	ds_read_b128 v[182:185], v192 offset:50176
	ds_read_b128 v[194:197], v192 offset:51200
	ds_read_b128 v[198:201], v192 offset:52224
	ds_read_b128 v[202:205], v192 offset:53248
	ds_read_b128 v[206:209], v192 offset:54272
	ds_read_b128 v[210:213], v192 offset:55296
	ds_read_b128 v[214:217], v192 offset:56320
	global_load_lds_dwordx4 v156, s[76:77]
	s_add_i32 m0, s18, 0x2000
	s_add_u32 s24, s38, 0x160080
	s_addc_u32 s25, s39, 0
	s_add_i32 s18, s19, s45
	global_load_lds_dwordx4 v160, s[76:77]
	s_mov_b32 m0, s18
	s_nop 0
	global_load_lds_dwordx4 v156, s[24:25]
	s_add_i32 m0, s18, 0x2000
	s_nop 0
	global_load_lds_dwordx4 v160, s[24:25]
	s_waitcnt lgkmcnt(0)
	s_barrier
	s_waitcnt lgkmcnt(0)
	v_mfma_f32_16x16x32_bf16 v[62:65], v[130:133], v[178:181], v[62:65]
	v_mfma_f32_16x16x32_bf16 v[58:61], v[138:141], v[178:181], v[58:61]
	v_mfma_f32_16x16x32_bf16 v[46:49], v[130:133], v[194:197], v[46:49]
	v_mfma_f32_16x16x32_bf16 v[42:45], v[138:141], v[194:197], v[42:45]
	v_mfma_f32_16x16x32_bf16 v[30:33], v[130:133], v[202:205], v[30:33]
	v_mfma_f32_16x16x32_bf16 v[26:29], v[138:141], v[202:205], v[26:29]
	v_mfma_f32_16x16x32_bf16 v[14:17], v[130:133], v[210:213], v[14:17]
	v_mfma_f32_16x16x32_bf16 v[10:13], v[138:141], v[210:213], v[10:13]
	v_mfma_f32_16x16x32_bf16 v[62:65], v[134:137], v[182:185], v[62:65]
	v_mfma_f32_16x16x32_bf16 v[58:61], v[142:145], v[182:185], v[58:61]
	v_mfma_f32_16x16x32_bf16 v[46:49], v[134:137], v[198:201], v[46:49]
	v_mfma_f32_16x16x32_bf16 v[42:45], v[142:145], v[198:201], v[42:45]
	v_mfma_f32_16x16x32_bf16 v[30:33], v[134:137], v[206:209], v[30:33]
	v_mfma_f32_16x16x32_bf16 v[26:29], v[142:145], v[206:209], v[26:29]
	v_mfma_f32_16x16x32_bf16 v[14:17], v[134:137], v[214:217], v[14:17]
	v_mfma_f32_16x16x32_bf16 v[10:13], v[142:145], v[214:217], v[10:13]
	v_mfma_f32_16x16x32_bf16 v[54:57], v[146:149], v[178:181], v[54:57]
	v_mfma_f32_16x16x32_bf16 v[50:53], v[170:173], v[178:181], v[50:53]
	v_mfma_f32_16x16x32_bf16 v[38:41], v[146:149], v[194:197], v[38:41]
	v_mfma_f32_16x16x32_bf16 v[34:37], v[170:173], v[194:197], v[34:37]
	v_mfma_f32_16x16x32_bf16 v[22:25], v[146:149], v[202:205], v[22:25]
	v_mfma_f32_16x16x32_bf16 v[18:21], v[170:173], v[202:205], v[18:21]
	v_mfma_f32_16x16x32_bf16 v[6:9], v[146:149], v[210:213], v[6:9]
	v_mfma_f32_16x16x32_bf16 v[2:5], v[170:173], v[210:213], v[2:5]
	v_mfma_f32_16x16x32_bf16 v[54:57], v[150:153], v[182:185], v[54:57]
	v_mfma_f32_16x16x32_bf16 v[50:53], v[174:177], v[182:185], v[50:53]
	v_mfma_f32_16x16x32_bf16 v[38:41], v[150:153], v[198:201], v[38:41]
	v_mfma_f32_16x16x32_bf16 v[34:37], v[174:177], v[198:201], v[34:37]
	v_mfma_f32_16x16x32_bf16 v[22:25], v[150:153], v[206:209], v[22:25]
	v_mfma_f32_16x16x32_bf16 v[18:21], v[174:177], v[206:209], v[18:21]
	v_mfma_f32_16x16x32_bf16 v[6:9], v[150:153], v[214:217], v[6:9]
	v_mfma_f32_16x16x32_bf16 v[2:5], v[174:177], v[214:217], v[2:5]
	s_waitcnt vmcnt(6)
	s_barrier
	s_add_i32 s63, s63, 2
	s_add_u32 s61, s61, 0x100
	s_addc_u32 s62, s62, 0
	s_cmpk_gt_u32 s63, 0x55
	s_mov_b64 s[24:25], s[36:37]
	s_cbranch_scc0 .LBB0_1127
	s_branch .Lkafter_5
